# past sub-tile loop: first two K fragments of the next sub-tile read from LDS at the end of the current one
# speedup vs baseline: 1.0130x; 1.0052x over previous
.LBB0_258:
	v_mov_b32_e32 v16, v143
	v_add_u32_e32 v143, 8, v16
	v_cmp_lt_i32_e32 vcc, v143, v135
	s_mov_b64 s[28:29], s[20:21]
	v_mov_b32_e32 v161, v141
	v_cndmask_b32_e32 v16, v16, v143, vcc
	v_lshl_or_b32 v18, v16, 5, v146
	v_cmp_lt_i32_e64 s[20:21], v18, v133
	s_mov_b64 s[26:27], s[24:25]
	v_mov_b32_e32 v151, v149
	v_cndmask_b32_e64 v16, 0, v18, s[20:21]
	v_ashrrev_i32_e32 v17, 31, v16
	v_lshl_add_u64 v[16:17], v[16:17], 1, s[18:19]
	global_load_ushort v141, v[16:17], off
	v_or_b32_e32 v16, 16, v18
	v_cmp_lt_i32_e64 s[24:25], v16, v133
	v_mov_b32_e32 v162, v137
	v_mov_b32_e32 v160, v139
	v_cndmask_b32_e64 v16, 0, v16, s[24:25]
	v_ashrrev_i32_e32 v17, 31, v16
	v_lshl_add_u64 v[16:17], v[16:17], 1, s[18:19]
	global_load_ushort v149, v[16:17], off
	s_waitcnt vmcnt(14)
	v_mov_b64_e32 v[46:47], v[6:7]
	s_waitcnt vmcnt(12)
	v_mov_b64_e32 v[34:35], v[14:15]
	v_mov_b64_e32 v[44:45], v[4:5]
	v_mov_b64_e32 v[32:33], v[12:13]
	v_mov_b64_e32 v[38:39], v[10:11]
	v_mov_b64_e32 v[42:43], v[2:3]
	v_mov_b64_e32 v[36:37], v[8:9]
	v_mov_b64_e32 v[40:41], v[0:1]
	v_cmp_ge_i32_e32 vcc, v143, v135
	v_mov_b32_e32 v158, 0
	s_mov_b32 s0, 0
	s_or_b64 s[22:23], vcc, s[22:23]
	v_mov_b32_e32 v166, 0xf149f2ca
	v_mov_b32_e32 v159, v158
	v_mov_b32_e32 v164, 0xf149f2ca
	v_mov_b32_e32 v60, v158
	v_mov_b32_e32 v61, v158
	v_mov_b32_e32 v62, v158
	v_mov_b32_e32 v63, v158
	v_mov_b32_e32 v56, v158
	v_mov_b32_e32 v57, v158
	v_mov_b32_e32 v58, v158
	v_mov_b32_e32 v59, v158
	v_mov_b32_e32 v52, v158
	v_mov_b32_e32 v53, v158
	v_mov_b32_e32 v54, v158
	v_mov_b32_e32 v55, v158
	v_mov_b32_e32 v48, v158
	v_mov_b32_e32 v49, v158
	v_mov_b32_e32 v50, v158
	v_mov_b32_e32 v51, v158
	v_mov_b32_e32 v28, v158
	v_mov_b32_e32 v29, v158
	v_mov_b32_e32 v30, v158
	v_mov_b32_e32 v31, v158
	v_mov_b32_e32 v24, v158
	v_mov_b32_e32 v25, v158
	v_mov_b32_e32 v26, v158
	v_mov_b32_e32 v27, v158
	v_mov_b32_e32 v20, v158
	v_mov_b32_e32 v21, v158
	v_mov_b32_e32 v22, v158
	v_mov_b32_e32 v23, v158
	v_mov_b32_e32 v16, v158
	v_mov_b32_e32 v17, v158
	v_mov_b32_e32 v18, v158
	v_mov_b32_e32 v19, v158
	v_mov_b32_e32 v116, v125
	ds_read_b128 v[234:237], v116 offset:2304
	ds_read_b128 v[238:241], v116
.LBB0_259:
	ds_read_b128 v[72:75], v116 offset:64
	ds_read_b128 v[100:103], v116 offset:2368
	v_mov_b32_e32 v163, v164
	v_add_u32_e32 v164, s0, v121
	s_waitcnt lgkmcnt(2)
	v_mfma_f32_16x16x32_bf16 v[198:201], v[234:237], v[40:43], 0
	v_mov_b32_e32 v165, v166
	v_add_u32_e32 v166, 0x2000, v164
	v_add_u32_e32 v167, 0x4000, v164
	v_mfma_f32_16x16x32_bf16 v[104:107], v[234:237], v[36:39], 0
	ds_read_b128 v[80:83], v116 offset:4608
	ds_read_b128 v[76:79], v116 offset:4672
	s_addk_i32 s0, 0x80
	s_cmpk_eq_i32 s0, 0x200
	v_mfma_f32_16x16x32_bf16 v[68:71], v[238:241], v[40:43], 0
	v_mfma_f32_16x16x32_bf16 v[64:67], v[238:241], v[36:39], 0
	s_waitcnt lgkmcnt(1)
	v_mfma_f32_16x16x32_bf16 v[92:95], v[80:83], v[40:43], 0
	v_mfma_f32_16x16x32_bf16 v[84:87], v[80:83], v[36:39], 0
	ds_read_b128 v[88:91], v116 offset:6912
	ds_read_b128 v[80:83], v116 offset:6976
	v_add_u32_e32 v116, 0x2400, v116
	s_waitcnt lgkmcnt(1)
	v_mfma_f32_16x16x32_bf16 v[96:99], v[88:91], v[40:43], 0
	v_mfma_f32_16x16x32_bf16 v[88:91], v[88:91], v[36:39], 0
	v_mfma_f32_16x16x32_bf16 v[68:71], v[72:75], v[44:47], v[68:71]
	v_mfma_f32_16x16x32_bf16 v[72:75], v[72:75], v[32:35], v[64:67]
	v_mfma_f32_16x16x32_bf16 v[64:67], v[100:103], v[44:47], v[198:201]
	v_mfma_f32_16x16x32_bf16 v[100:103], v[100:103], v[32:35], v[104:107]
	s_nop 2
	ds_read2_b64 v[104:107], v164 offset1:4
	ds_read2_b64 v[198:201], v164 offset0:8 offset1:12
	v_add_u32_e32 v164, 0x6000, v164
	v_mfma_f32_16x16x32_bf16 v[92:95], v[76:79], v[44:47], v[92:95]
	v_mfma_f32_16x16x32_bf16 v[76:79], v[76:79], v[32:35], v[84:87]
	s_nop 2
	ds_read2_b64 v[84:87], v166 offset0:32 offset1:36
	ds_read2_b64 v[202:205], v166 offset0:40 offset1:44
	ds_read2_b64 v[206:209], v167 offset0:64 offset1:68
	ds_read2_b64 v[210:213], v167 offset0:72 offset1:76
	ds_read2_b64 v[214:217], v164 offset0:96 offset1:100
	ds_read2_b64 v[218:221], v164 offset0:104 offset1:108
	s_waitcnt lgkmcnt(8)
	v_mfma_f32_16x16x32_bf16 v[96:99], v[80:83], v[44:47], v[96:99]
	v_mfma_f32_16x16x32_bf16 v[80:83], v[80:83], v[32:35], v[88:91]
	s_nop 2
	v_max3_f32 v88, v68, s4, v69
	v_max3_f32 v89, v72, s4, v73
	v_max3_f32 v88, v88, v70, v71
	v_max3_f32 v89, v89, v74, v75
	v_max3_f32 v88, v88, v64, v65
	v_max3_f32 v89, v89, v100, v101
	v_max3_f32 v88, v88, v66, v67
	v_max3_f32 v89, v89, v102, v103
	v_max3_f32 v88, v88, v92, v93
	v_max3_f32 v89, v89, v76, v77
	v_max3_f32 v88, v88, v94, v95
	v_max3_f32 v89, v89, v78, v79
	v_max3_f32 v88, v88, v96, v97
	v_max3_f32 v89, v89, v80, v81
	v_max3_f32 v88, v88, v98, v99
	v_max3_f32 v89, v89, v82, v83
	v_mov_b32_e32 v90, v88
	v_mov_b32_e32 v91, v89
	s_nop 0
	v_permlane16_swap_b32_e32 v90, v88
	v_permlane16_swap_b32_e32 v91, v89
	v_max_f32_e32 v88, v88, v90
	v_max_f32_e32 v89, v89, v91
	v_mov_b32_e32 v90, v88
	v_mov_b32_e32 v91, v89
	s_nop 0
	v_permlane32_swap_b32_e32 v90, v88
	v_permlane32_swap_b32_e32 v91, v89
	v_max3_f32 v164, v163, v89, v91
	v_max3_f32 v166, v165, v88, v90
	v_sub_f32_e32 v89, v163, v164
	v_sub_f32_e32 v88, v165, v166
	v_sub_f32_e32 v68, v68, v166
	v_sub_f32_e32 v90, v72, v164
	v_sub_f32_e32 v69, v69, v166
	v_sub_f32_e32 v91, v73, v164
	v_sub_f32_e32 v70, v70, v166
	v_sub_f32_e32 v163, v74, v164
	v_sub_f32_e32 v71, v71, v166
	v_sub_f32_e32 v165, v75, v164
	v_sub_f32_e32 v64, v64, v166
	v_sub_f32_e32 v100, v100, v164
	v_sub_f32_e32 v65, v65, v166
	v_sub_f32_e32 v101, v101, v164
	v_sub_f32_e32 v66, v66, v166
	v_sub_f32_e32 v102, v102, v164
	v_sub_f32_e32 v67, v67, v166
	v_sub_f32_e32 v103, v103, v164
	v_exp_f32_e32 v73, v89
	v_sub_f32_e32 v167, v92, v166
	v_sub_f32_e32 v179, v76, v164
	v_sub_f32_e32 v178, v93, v166
	v_sub_f32_e32 v185, v77, v164
	v_sub_f32_e32 v187, v78, v164
	v_sub_f32_e32 v222, v79, v164
	v_sub_f32_e32 v224, v80, v164
	v_sub_f32_e32 v225, v81, v164
	v_sub_f32_e32 v227, v82, v164
	v_sub_f32_e32 v228, v83, v164
	v_exp_f32_e32 v72, v88
	v_exp_f32_e32 v74, v68
	v_exp_f32_e32 v75, v90
	v_exp_f32_e32 v76, v69
	v_exp_f32_e32 v77, v91
	v_exp_f32_e32 v78, v70
	v_exp_f32_e32 v79, v163
	v_exp_f32_e32 v80, v71
	v_exp_f32_e32 v81, v165
	v_exp_f32_e32 v82, v64
	v_exp_f32_e32 v83, v100
	v_exp_f32_e32 v88, v65
	v_exp_f32_e32 v89, v101
	v_exp_f32_e32 v90, v66
	v_exp_f32_e32 v91, v102
	v_exp_f32_e32 v92, v67
	v_exp_f32_e32 v93, v103
	v_sub_f32_e32 v186, v94, v166
	v_sub_f32_e32 v226, v98, v166
	v_exp_f32_e32 v98, v186
	v_mov_b32_e32 v186, v73
	v_sub_f32_e32 v95, v95, v166
	v_sub_f32_e32 v223, v96, v166
	v_sub_f32_e32 v97, v97, v166
	v_sub_f32_e32 v99, v99, v166
	v_pk_mul_f32 v[62:63], v[62:63], v[72:73] op_sel_hi:[1,0]
	v_pk_mul_f32 v[60:61], v[60:61], v[72:73] op_sel_hi:[1,0]
	v_pk_mul_f32 v[58:59], v[58:59], v[72:73] op_sel_hi:[1,0]
	v_cvt_pk_bf16_f32 v64, v74, v76
	v_cvt_pk_bf16_f32 v65, v78, v80
	v_cvt_pk_bf16_f32 v66, v82, v88
	v_cvt_pk_bf16_f32 v67, v90, v92
	v_pk_mul_f32 v[56:57], v[56:57], v[72:73] op_sel_hi:[1,0]
	v_cvt_pk_bf16_f32 v68, v75, v77
	v_cvt_pk_bf16_f32 v69, v79, v81
	v_cvt_pk_bf16_f32 v70, v83, v89
	v_cvt_pk_bf16_f32 v71, v91, v93
	v_pk_mul_f32 v[30:31], v[30:31], v[186:187] op_sel_hi:[1,0]
	v_pk_mul_f32 v[28:29], v[28:29], v[186:187] op_sel_hi:[1,0]
	v_pk_mul_f32 v[26:27], v[26:27], v[186:187] op_sel_hi:[1,0]
	v_pk_mul_f32 v[24:25], v[24:25], v[186:187] op_sel_hi:[1,0]
	v_exp_f32_e32 v94, v167
	v_exp_f32_e32 v96, v178
	v_exp_f32_e32 v100, v95
	v_exp_f32_e32 v102, v223
	v_exp_f32_e32 v178, v97
	s_waitcnt lgkmcnt(7)
	v_mfma_f32_16x16x32_bf16 v[60:63], v[104:107], v[64:67], v[60:63]
	v_mul_f32_e64 v54, v54, v72
	v_mul_f32_e64 v55, v55, v72
	v_pk_mul_f32 v[52:53], v[52:53], v[72:73] op_sel_hi:[1,0]
	v_pk_mul_f32 v[50:51], v[50:51], v[72:73] op_sel_hi:[1,0]
	s_waitcnt lgkmcnt(5)
	v_mfma_f32_16x16x32_bf16 v[56:59], v[84:87], v[64:67], v[56:59]
	v_mul_f32_e64 v48, v48, v72
	v_mul_f32_e64 v49, v49, v72
	v_exp_f32_e32 v95, v179
	v_exp_f32_e32 v97, v185
	v_mfma_f32_16x16x32_bf16 v[28:31], v[104:107], v[68:71], v[28:31]
	v_exp_f32_e32 v104, v226
	v_exp_f32_e32 v101, v222
	v_exp_f32_e32 v103, v224
	v_mfma_f32_16x16x32_bf16 v[24:27], v[84:87], v[68:71], v[24:27]
	v_exp_f32_e32 v84, v99
	v_exp_f32_e32 v99, v187
	v_exp_f32_e32 v179, v225
	s_waitcnt lgkmcnt(3)
	v_mfma_f32_16x16x32_bf16 v[52:55], v[206:209], v[64:67], v[52:55]
	v_exp_f32_e32 v105, v227
	v_pk_mul_f32 v[22:23], v[22:23], v[186:187] op_sel_hi:[1,0]
	v_pk_mul_f32 v[20:21], v[20:21], v[186:187] op_sel_hi:[1,0]
	s_waitcnt lgkmcnt(1)
	v_mfma_f32_16x16x32_bf16 v[48:51], v[214:217], v[64:67], v[48:51]
	v_cvt_pk_bf16_f32 v64, v94, v96
	v_cvt_pk_bf16_f32 v65, v98, v100
	v_cvt_pk_bf16_f32 v66, v102, v178
	v_cvt_pk_bf16_f32 v67, v104, v84
	v_pk_mul_f32 v[18:19], v[18:19], v[186:187] op_sel_hi:[1,0]
	v_pk_mul_f32 v[16:17], v[16:17], v[186:187] op_sel_hi:[1,0]
	v_mfma_f32_16x16x32_bf16 v[60:63], v[198:201], v[64:67], v[60:63]
	v_exp_f32_e32 v85, v228
	v_mfma_f32_16x16x32_bf16 v[56:59], v[202:205], v[64:67], v[56:59]
	v_mfma_f32_16x16x32_bf16 v[52:55], v[210:213], v[64:67], v[52:55]
	s_waitcnt lgkmcnt(0)
	v_mfma_f32_16x16x32_bf16 v[48:51], v[218:221], v[64:67], v[48:51]
	ds_read_b128 v[234:237], v116 offset:2304
	ds_read_b128 v[238:241], v116
	v_add_f32_e64 v64, v74, 0
	v_add_f32_e64 v65, v75, 0
	v_pk_add_f32 v[64:65], v[76:77], v[64:65]
	v_mfma_f32_16x16x32_bf16 v[20:23], v[206:209], v[68:71], v[20:23]
	v_add_f32_e64 v64, v78, v64
	v_add_f32_e64 v65, v79, v65
	v_pk_add_f32 v[64:65], v[80:81], v[64:65]
	v_mfma_f32_16x16x32_bf16 v[16:19], v[214:217], v[68:71], v[16:19]
	v_add_f32_e64 v64, v82, v64
	v_add_f32_e64 v65, v83, v65
	v_cvt_pk_bf16_f32 v68, v95, v97
	v_pk_add_f32 v[64:65], v[88:89], v[64:65]
	v_cvt_pk_bf16_f32 v69, v99, v101
	v_pk_add_f32 v[64:65], v[90:91], v[64:65]
	v_cvt_pk_bf16_f32 v70, v103, v179
	v_pk_add_f32 v[64:65], v[92:93], v[64:65]
	v_cvt_pk_bf16_f32 v71, v105, v85
	v_pk_add_f32 v[64:65], v[94:95], v[64:65]
	s_nop 0
	v_pk_add_f32 v[64:65], v[96:97], v[64:65]
	v_mfma_f32_16x16x32_bf16 v[28:31], v[198:201], v[68:71], v[28:31]
	v_add_f32_e64 v64, v98, v64
	v_add_f32_e64 v65, v99, v65
	v_pk_add_f32 v[64:65], v[100:101], v[64:65]
	v_mfma_f32_16x16x32_bf16 v[24:27], v[202:205], v[68:71], v[24:27]
	v_add_f32_e64 v64, v102, v64
	v_add_f32_e64 v65, v103, v65
	v_pk_add_f32 v[64:65], v[178:179], v[64:65]
	v_mfma_f32_16x16x32_bf16 v[20:23], v[210:213], v[68:71], v[20:23]
	v_add_f32_e64 v64, v104, v64
	v_add_f32_e64 v65, v105, v65
	v_pk_add_f32 v[64:65], v[84:85], v[64:65]
	v_mfma_f32_16x16x32_bf16 v[16:19], v[218:221], v[68:71], v[16:19]
	v_mov_b32_e32 v66, v64
	v_mov_b32_e32 v67, v65
	s_nop 0
	v_permlane16_swap_b32_e32 v66, v64
	v_permlane16_swap_b32_e32 v67, v65
	v_pk_add_f32 v[64:65], v[64:65], v[66:67]
	s_nop 0
	v_mov_b32_e32 v66, v64
	v_mov_b32_e32 v67, v65
	s_nop 0
	v_permlane32_swap_b32_e32 v66, v64
	v_permlane32_swap_b32_e32 v67, v65
	v_pk_add_f32 v[64:65], v[64:65], v[66:67]
	s_nop 0
	v_pk_fma_f32 v[158:159], v[158:159], v[72:73], v[64:65]
	s_cmpk_lg_i32 s0, 0x80
	s_cbranch_scc1 .Lpast_qskip
	s_cmp_lg_u64 s[22:23], 0
	s_cbranch_scc1 .Lpast_qskip
	v_mov_b32_e32 v233, 0
	s_waitcnt vmcnt(1)
	v_and_b32_e32 v137, 0xfff, v141
	v_lshlrev_b32_e32 v232, 7, v137
	v_lshl_add_u64 v[4:5], v[156:157], 0, v[232:233]
	global_load_dwordx4 v[0:3], v[4:5], off
	s_nop 0
	global_load_dwordx4 v[4:7], v[4:5], off offset:64
	s_waitcnt vmcnt(2)
	v_and_b32_e32 v139, 0xfff, v149
	v_lshlrev_b32_e32 v232, 7, v139
	v_lshl_add_u64 v[12:13], v[156:157], 0, v[232:233]
	global_load_dwordx4 v[8:11], v[12:13], off
	s_nop 0
	global_load_dwordx4 v[12:15], v[12:13], off offset:64
